# v56 + attention band-tile causal mask blocks in the step loops: one subtraction plus (compare-with-constant, select) per score with three rotating mask registers (66 instrs instead of 128, no nops)
# baseline (speedup 1.0000x reference)
.Lattn_rare_m0_c3:
	v_sub_u32_e32 v67, v185, v187
	v_cmp_le_i32_e32 vcc, 32, v67
	v_cmp_le_i32_e64 s[4:5], 1, v67
	v_cmp_le_i32_e64 s[22:23], 0, v67
	v_cndmask_b32_e32 v114, v206, v114, vcc
	v_cmp_le_i32_e32 vcc, 33, v67
	v_cndmask_b32_e64 v131, v206, v131, s[4:5]
	v_cmp_le_i32_e64 s[4:5], 2, v67
	v_cndmask_b32_e64 v130, v206, v130, s[22:23]
	v_cmp_le_i32_e64 s[22:23], 34, v67
	v_cndmask_b32_e32 v115, v206, v115, vcc
	v_cmp_le_i32_e32 vcc, 3, v67
	v_cndmask_b32_e64 v132, v206, v132, s[4:5]
	v_cmp_le_i32_e64 s[4:5], 35, v67
	v_cndmask_b32_e64 v116, v206, v116, s[22:23]
	v_cmp_le_i32_e64 s[22:23], 8, v67
	v_cndmask_b32_e32 v133, v206, v133, vcc
	v_cmp_le_i32_e32 vcc, 40, v67
	v_cndmask_b32_e64 v117, v206, v117, s[4:5]
	v_cmp_le_i32_e64 s[4:5], 9, v67
	v_cndmask_b32_e64 v134, v206, v134, s[22:23]
	v_cmp_le_i32_e64 s[22:23], 41, v67
	v_cndmask_b32_e32 v118, v206, v118, vcc
	v_cmp_le_i32_e32 vcc, 10, v67
	v_cndmask_b32_e64 v135, v206, v135, s[4:5]
	v_cmp_le_i32_e64 s[4:5], 42, v67
	v_cndmask_b32_e64 v119, v206, v119, s[22:23]
	v_cmp_le_i32_e64 s[22:23], 11, v67
	v_cndmask_b32_e32 v136, v206, v136, vcc
	v_cmp_le_i32_e32 vcc, 43, v67
	v_cndmask_b32_e64 v120, v206, v120, s[4:5]
	v_cmp_le_i32_e64 s[4:5], 16, v67
	v_cndmask_b32_e64 v137, v206, v137, s[22:23]
	v_cmp_le_i32_e64 s[22:23], 48, v67
	v_cndmask_b32_e32 v121, v206, v121, vcc
	v_cmp_le_i32_e32 vcc, 17, v67
	v_cndmask_b32_e64 v138, v206, v138, s[4:5]
	v_cmp_le_i32_e64 s[4:5], 49, v67
	v_cndmask_b32_e64 v122, v206, v122, s[22:23]
	v_cmp_le_i32_e64 s[22:23], 18, v67
	v_cndmask_b32_e32 v139, v206, v139, vcc
	v_cmp_le_i32_e32 vcc, 50, v67
	v_cndmask_b32_e64 v123, v206, v123, s[4:5]
	v_cmp_le_i32_e64 s[4:5], 19, v67
	v_cndmask_b32_e64 v140, v206, v140, s[22:23]
	v_cmp_le_i32_e64 s[22:23], 51, v67
	v_cndmask_b32_e32 v124, v206, v124, vcc
	v_cmp_le_i32_e32 vcc, 24, v67
	v_cndmask_b32_e64 v141, v206, v141, s[4:5]
	v_cmp_le_i32_e64 s[4:5], 56, v67
	v_cndmask_b32_e64 v125, v206, v125, s[22:23]
	v_cmp_le_i32_e64 s[22:23], 25, v67
	v_cndmask_b32_e32 v142, v206, v142, vcc
	v_cmp_le_i32_e32 vcc, 57, v67
	v_cndmask_b32_e64 v126, v206, v126, s[4:5]
	v_cmp_le_i32_e64 s[4:5], 26, v67
	v_cndmask_b32_e64 v143, v206, v143, s[22:23]
	v_cmp_le_i32_e64 s[22:23], 58, v67
	v_cndmask_b32_e32 v127, v206, v127, vcc
	v_cmp_le_i32_e32 vcc, 27, v67
	v_cndmask_b32_e64 v144, v206, v144, s[4:5]
	v_cmp_le_i32_e64 s[4:5], 59, v67
	v_cndmask_b32_e64 v128, v206, v128, s[22:23]
	v_cndmask_b32_e32 v145, v206, v145, vcc
	v_cndmask_b32_e64 v129, v206, v129, s[4:5]
	s_branch .LBB0_797

.Lattn_rare_m0_c6:
	v_sub_u32_e32 v123, v185, v187
	v_add_u32_e32 v124, 0xffffffc0, v123
	v_cmp_le_i32_e32 vcc, 32, v124
	v_cmp_le_i32_e64 s[4:5], 1, v124
	v_cmp_le_i32_e64 s[22:23], 64, v123
	v_cndmask_b32_e32 v66, v206, v66, vcc
	v_cmp_le_i32_e32 vcc, 33, v124
	v_cndmask_b32_e64 v99, v206, v99, s[4:5]
	v_cmp_le_i32_e64 s[4:5], 2, v124
	v_cndmask_b32_e64 v98, v206, v98, s[22:23]
	v_cmp_le_i32_e64 s[22:23], 34, v124
	v_cndmask_b32_e32 v67, v206, v67, vcc
	v_cmp_le_i32_e32 vcc, 3, v124
	v_cndmask_b32_e64 v100, v206, v100, s[4:5]
	v_cmp_le_i32_e64 s[4:5], 35, v124
	v_cndmask_b32_e64 v68, v206, v68, s[22:23]
	v_cmp_le_i32_e64 s[22:23], 8, v124
	v_cndmask_b32_e32 v101, v206, v101, vcc
	v_cmp_le_i32_e32 vcc, 40, v124
	v_cndmask_b32_e64 v69, v206, v69, s[4:5]
	v_cmp_le_i32_e64 s[4:5], 9, v124
	v_cndmask_b32_e64 v102, v206, v102, s[22:23]
	v_cmp_le_i32_e64 s[22:23], 41, v124
	v_cndmask_b32_e32 v70, v206, v70, vcc
	v_cmp_le_i32_e32 vcc, 10, v124
	v_cndmask_b32_e64 v103, v206, v103, s[4:5]
	v_cmp_le_i32_e64 s[4:5], 42, v124
	v_cndmask_b32_e64 v71, v206, v71, s[22:23]
	v_cmp_le_i32_e64 s[22:23], 11, v124
	v_cndmask_b32_e32 v104, v206, v104, vcc
	v_cmp_le_i32_e32 vcc, 43, v124
	v_cndmask_b32_e64 v72, v206, v72, s[4:5]
	v_cmp_le_i32_e64 s[4:5], 16, v124
	v_cndmask_b32_e64 v105, v206, v105, s[22:23]
	v_cmp_le_i32_e64 s[22:23], 48, v124
	v_cndmask_b32_e32 v73, v206, v73, vcc
	v_cmp_le_i32_e32 vcc, 17, v124
	v_cndmask_b32_e64 v106, v206, v106, s[4:5]
	v_cmp_le_i32_e64 s[4:5], 49, v124
	v_cndmask_b32_e64 v74, v206, v74, s[22:23]
	v_cmp_le_i32_e64 s[22:23], 18, v124
	v_cndmask_b32_e32 v107, v206, v107, vcc
	v_cmp_le_i32_e32 vcc, 50, v124
	v_cndmask_b32_e64 v75, v206, v75, s[4:5]
	v_cmp_le_i32_e64 s[4:5], 19, v124
	v_cndmask_b32_e64 v108, v206, v108, s[22:23]
	v_cmp_le_i32_e64 s[22:23], 51, v124
	v_cndmask_b32_e32 v76, v206, v76, vcc
	v_cmp_le_i32_e32 vcc, 24, v124
	v_cndmask_b32_e64 v109, v206, v109, s[4:5]
	v_cmp_le_i32_e64 s[4:5], 56, v124
	v_cndmask_b32_e64 v77, v206, v77, s[22:23]
	v_cmp_le_i32_e64 s[22:23], 25, v124
	v_cndmask_b32_e32 v110, v206, v110, vcc
	v_cmp_le_i32_e32 vcc, 57, v124
	v_cndmask_b32_e64 v78, v206, v78, s[4:5]
	v_cmp_le_i32_e64 s[4:5], 26, v124
	v_cndmask_b32_e64 v111, v206, v111, s[22:23]
	v_cmp_le_i32_e64 s[22:23], 58, v124
	v_cndmask_b32_e32 v79, v206, v79, vcc
	v_cmp_le_i32_e32 vcc, 27, v124
	v_cndmask_b32_e64 v112, v206, v112, s[4:5]
	v_cmp_le_i32_e64 s[4:5], 59, v124
	v_cndmask_b32_e64 v80, v206, v80, s[22:23]
	v_cndmask_b32_e32 v113, v206, v113, vcc
	v_cndmask_b32_e64 v81, v206, v81, s[4:5]
	s_branch .LBB0_810

.Lattn_rare_m1_c3:
	v_sub_u32_e32 v67, v212, v185
	v_cmp_le_i32_e32 vcc, 32, v67
	v_cmp_le_i32_e64 s[4:5], 1, v67
	v_cmp_le_i32_e64 s[22:23], 0, v67
	v_cndmask_b32_e32 v114, v206, v114, vcc
	v_cmp_le_i32_e32 vcc, 33, v67
	v_cndmask_b32_e64 v131, v206, v131, s[4:5]
	v_cmp_le_i32_e64 s[4:5], 2, v67
	v_cndmask_b32_e64 v130, v206, v130, s[22:23]
	v_cmp_le_i32_e64 s[22:23], 34, v67
	v_cndmask_b32_e32 v115, v206, v115, vcc
	v_cmp_le_i32_e32 vcc, 3, v67
	v_cndmask_b32_e64 v132, v206, v132, s[4:5]
	v_cmp_le_i32_e64 s[4:5], 35, v67
	v_cndmask_b32_e64 v116, v206, v116, s[22:23]
	v_cmp_le_i32_e64 s[22:23], 8, v67
	v_cndmask_b32_e32 v133, v206, v133, vcc
	v_cmp_le_i32_e32 vcc, 40, v67
	v_cndmask_b32_e64 v117, v206, v117, s[4:5]
	v_cmp_le_i32_e64 s[4:5], 9, v67
	v_cndmask_b32_e64 v134, v206, v134, s[22:23]
	v_cmp_le_i32_e64 s[22:23], 41, v67
	v_cndmask_b32_e32 v118, v206, v118, vcc
	v_cmp_le_i32_e32 vcc, 10, v67
	v_cndmask_b32_e64 v135, v206, v135, s[4:5]
	v_cmp_le_i32_e64 s[4:5], 42, v67
	v_cndmask_b32_e64 v119, v206, v119, s[22:23]
	v_cmp_le_i32_e64 s[22:23], 11, v67
	v_cndmask_b32_e32 v136, v206, v136, vcc
	v_cmp_le_i32_e32 vcc, 43, v67
	v_cndmask_b32_e64 v120, v206, v120, s[4:5]
	v_cmp_le_i32_e64 s[4:5], 16, v67
	v_cndmask_b32_e64 v137, v206, v137, s[22:23]
	v_cmp_le_i32_e64 s[22:23], 48, v67
	v_cndmask_b32_e32 v121, v206, v121, vcc
	v_cmp_le_i32_e32 vcc, 17, v67
	v_cndmask_b32_e64 v138, v206, v138, s[4:5]
	v_cmp_le_i32_e64 s[4:5], 49, v67
	v_cndmask_b32_e64 v122, v206, v122, s[22:23]
	v_cmp_le_i32_e64 s[22:23], 18, v67
	v_cndmask_b32_e32 v139, v206, v139, vcc
	v_cmp_le_i32_e32 vcc, 50, v67
	v_cndmask_b32_e64 v123, v206, v123, s[4:5]
	v_cmp_le_i32_e64 s[4:5], 19, v67
	v_cndmask_b32_e64 v140, v206, v140, s[22:23]
	v_cmp_le_i32_e64 s[22:23], 51, v67
	v_cndmask_b32_e32 v124, v206, v124, vcc
	v_cmp_le_i32_e32 vcc, 24, v67
	v_cndmask_b32_e64 v141, v206, v141, s[4:5]
	v_cmp_le_i32_e64 s[4:5], 56, v67
	v_cndmask_b32_e64 v125, v206, v125, s[22:23]
	v_cmp_le_i32_e64 s[22:23], 25, v67
	v_cndmask_b32_e32 v142, v206, v142, vcc
	v_cmp_le_i32_e32 vcc, 57, v67
	v_cndmask_b32_e64 v126, v206, v126, s[4:5]
	v_cmp_le_i32_e64 s[4:5], 26, v67
	v_cndmask_b32_e64 v143, v206, v143, s[22:23]
	v_cmp_le_i32_e64 s[22:23], 58, v67
	v_cndmask_b32_e32 v127, v206, v127, vcc
	v_cmp_le_i32_e32 vcc, 27, v67
	v_cndmask_b32_e64 v144, v206, v144, s[4:5]
	v_cmp_le_i32_e64 s[4:5], 59, v67
	v_cndmask_b32_e64 v128, v206, v128, s[22:23]
	v_cndmask_b32_e32 v145, v206, v145, vcc
	v_cndmask_b32_e64 v129, v206, v129, s[4:5]
	s_branch .LBB0_865

.Lattn_rare_m1_c6:
	v_sub_u32_e32 v123, v212, v185
	v_add_u32_e32 v124, 0xffffffc0, v123
	v_cmp_le_i32_e32 vcc, 32, v124
	v_cmp_le_i32_e64 s[4:5], 1, v124
	v_cmp_le_i32_e64 s[22:23], 64, v123
	v_cndmask_b32_e32 v66, v206, v66, vcc
	v_cmp_le_i32_e32 vcc, 33, v124
	v_cndmask_b32_e64 v99, v206, v99, s[4:5]
	v_cmp_le_i32_e64 s[4:5], 2, v124
	v_cndmask_b32_e64 v98, v206, v98, s[22:23]
	v_cmp_le_i32_e64 s[22:23], 34, v124
	v_cndmask_b32_e32 v67, v206, v67, vcc
	v_cmp_le_i32_e32 vcc, 3, v124
	v_cndmask_b32_e64 v100, v206, v100, s[4:5]
	v_cmp_le_i32_e64 s[4:5], 35, v124
	v_cndmask_b32_e64 v68, v206, v68, s[22:23]
	v_cmp_le_i32_e64 s[22:23], 8, v124
	v_cndmask_b32_e32 v101, v206, v101, vcc
	v_cmp_le_i32_e32 vcc, 40, v124
	v_cndmask_b32_e64 v69, v206, v69, s[4:5]
	v_cmp_le_i32_e64 s[4:5], 9, v124
	v_cndmask_b32_e64 v102, v206, v102, s[22:23]
	v_cmp_le_i32_e64 s[22:23], 41, v124
	v_cndmask_b32_e32 v70, v206, v70, vcc
	v_cmp_le_i32_e32 vcc, 10, v124
	v_cndmask_b32_e64 v103, v206, v103, s[4:5]
	v_cmp_le_i32_e64 s[4:5], 42, v124
	v_cndmask_b32_e64 v71, v206, v71, s[22:23]
	v_cmp_le_i32_e64 s[22:23], 11, v124
	v_cndmask_b32_e32 v104, v206, v104, vcc
	v_cmp_le_i32_e32 vcc, 43, v124
	v_cndmask_b32_e64 v72, v206, v72, s[4:5]
	v_cmp_le_i32_e64 s[4:5], 16, v124
	v_cndmask_b32_e64 v105, v206, v105, s[22:23]
	v_cmp_le_i32_e64 s[22:23], 48, v124
	v_cndmask_b32_e32 v73, v206, v73, vcc
	v_cmp_le_i32_e32 vcc, 17, v124
	v_cndmask_b32_e64 v106, v206, v106, s[4:5]
	v_cmp_le_i32_e64 s[4:5], 49, v124
	v_cndmask_b32_e64 v74, v206, v74, s[22:23]
	v_cmp_le_i32_e64 s[22:23], 18, v124
	v_cndmask_b32_e32 v107, v206, v107, vcc
	v_cmp_le_i32_e32 vcc, 50, v124
	v_cndmask_b32_e64 v75, v206, v75, s[4:5]
	v_cmp_le_i32_e64 s[4:5], 19, v124
	v_cndmask_b32_e64 v108, v206, v108, s[22:23]
	v_cmp_le_i32_e64 s[22:23], 51, v124
	v_cndmask_b32_e32 v76, v206, v76, vcc
	v_cmp_le_i32_e32 vcc, 24, v124
	v_cndmask_b32_e64 v109, v206, v109, s[4:5]
	v_cmp_le_i32_e64 s[4:5], 56, v124
	v_cndmask_b32_e64 v77, v206, v77, s[22:23]
	v_cmp_le_i32_e64 s[22:23], 25, v124
	v_cndmask_b32_e32 v110, v206, v110, vcc
	v_cmp_le_i32_e32 vcc, 57, v124
	v_cndmask_b32_e64 v78, v206, v78, s[4:5]
	v_cmp_le_i32_e64 s[4:5], 26, v124
	v_cndmask_b32_e64 v111, v206, v111, s[22:23]
	v_cmp_le_i32_e64 s[22:23], 58, v124
	v_cndmask_b32_e32 v79, v206, v79, vcc
	v_cmp_le_i32_e32 vcc, 27, v124
	v_cndmask_b32_e64 v112, v206, v112, s[4:5]
	v_cmp_le_i32_e64 s[4:5], 59, v124
	v_cndmask_b32_e64 v80, v206, v80, s[22:23]
	v_cndmask_b32_e32 v113, v206, v113, vcc
	v_cndmask_b32_e64 v81, v206, v81, s[4:5]
	s_branch .LBB0_878
